# v37 + defer consuming the work-queue atomic result until the unit's first full load wait (no exposed atomic round trip per item)
# speedup vs baseline: 1.0028x; 1.0028x over previous
.LBB0_503:
	v_mov_b32_e32 v164, 0
	s_and_saveexec_b64 s[0:1], s[96:97]
	s_cbranch_execz .LBB0_507
	s_mov_b64 s[4:5], exec
	v_mbcnt_lo_u32_b32 v0, s4, 0
	v_mbcnt_hi_u32_b32 v0, s5, v0
	v_cmp_eq_u32_e32 vcc, 0, v0
	s_and_saveexec_b64 s[2:3], vcc
	s_cbranch_execz .LBB0_506
	s_bcnt1_i32_b64 s4, s[4:5]
	v_mov_b32_e32 v2, s4
	v_readlane_b32 s4, v249, 57
	v_readlane_b32 s5, v249, 58
	s_nop 4
	global_atomic_add v203, v1, v2, s[4:5] sc0

.LBB0_550:
	s_or_b64 exec, exec, s[0:1]
	v_add_u32_e32 v0, 1, v128
	v_cvt_f32_u32_e32 v0, v0
	v_mov_b32_e32 v95, v97
	v_mov_b32_e32 v97, v103
	v_mov_b32_e32 v79, v85
	v_exp_f32_e64 v0, -v0
	v_mov_b32_e32 v85, v101
	v_mov_b32_e32 v87, v93
	v_mov_b32_e32 v93, v113
	v_mul_f32_e32 v118, 0x3fb8aa3b, v0
	v_add_f32_e32 v0, v99, v102
	v_fmamk_f32 v0, v0, 0x3c800000, v154
	v_rsq_f32_e32 v0, v0
	v_mov_b32_e32 v99, v67
	v_mov_b32_e32 v77, v89
	v_mov_b32_e32 v89, v117
	v_mul_f32_e32 v0, 0x3e38aa3b, v0
	s_waitcnt vmcnt(0)
	v_readfirstlane_b32 s32, v203
	s_add_i32 s32, s88, s32
	s_nop 0
	v_mov_b32_e32 v164, s32
	v_pk_mul_f32 v[34:35], v[0:1], v[98:99] op_sel_hi:[0,1]
	v_pk_mul_f32 v[30:31], v[30:31], v[34:35]
	v_pk_mul_f32 v[34:35], v[0:1], v[96:97] op_sel_hi:[0,1]
	v_pk_mul_f32 v[32:33], v[32:33], v[34:35]
	v_pk_mul_f32 v[34:35], v[0:1], v[84:85] op_sel_hi:[0,1]
	v_pk_mul_f32 v[26:27], v[26:27], v[34:35]
	v_mov_b32_e32 v75, v109
	v_cvt_pk_bf16_f32 v84, v26, v27
	v_pk_mul_f32 v[26:27], v[0:1], v[94:95] op_sel_hi:[0,1]
	v_pk_mul_f32 v[22:23], v[22:23], v[26:27]
	v_pk_mul_f32 v[26:27], v[0:1], v[92:93] op_sel_hi:[0,1]
	v_pk_mul_f32 v[24:25], v[24:25], v[26:27]
	v_pk_mul_f32 v[26:27], v[0:1], v[88:89] op_sel_hi:[0,1]
	v_pk_mul_f32 v[18:19], v[18:19], v[26:27]
	v_mov_b32_e32 v71, v105
	v_cvt_pk_bf16_f32 v88, v18, v19
	v_pk_mul_f32 v[18:19], v[0:1], v[90:91] op_sel_hi:[0,1]
	v_pk_mul_f32 v[14:15], v[14:15], v[18:19]
	v_pk_mul_f32 v[18:19], v[0:1], v[80:81] op_sel_hi:[0,1]
	v_pk_mul_f32 v[16:17], v[16:17], v[18:19]
	v_pk_mul_f32 v[18:19], v[0:1], v[78:79] op_sel_hi:[0,1]
	v_pk_mul_f32 v[10:11], v[10:11], v[18:19]
	v_mov_b32_e32 v83, v111
	v_cvt_pk_bf16_f32 v92, v10, v11
	v_pk_mul_f32 v[10:11], v[0:1], v[74:75] op_sel_hi:[0,1]
	v_pk_mul_f32 v[6:7], v[6:7], v[10:11]
	v_pk_mul_f32 v[10:11], v[0:1], v[72:73] op_sel_hi:[0,1]
	v_pk_mul_f32 v[8:9], v[8:9], v[10:11]
	v_pk_mul_f32 v[10:11], v[0:1], v[70:71] op_sel_hi:[0,1]
	v_lshlrev_b32_e32 v119, 2, v170
	v_pk_mul_f32 v[34:35], v[0:1], v[82:83] op_sel_hi:[0,1]
	v_pk_mul_f32 v[26:27], v[0:1], v[86:87] op_sel_hi:[0,1]
	v_pk_mul_f32 v[18:19], v[0:1], v[76:77] op_sel_hi:[0,1]
	v_pk_mul_f32 v[2:3], v[2:3], v[10:11]
	v_pk_mul_f32 v[10:11], v[0:1], v[68:69] op_sel_hi:[0,1]
	v_or_b32_e32 v0, 1, v119
	v_cvt_pk_bf16_f32 v96, v2, v3
	v_cvt_f32_ubyte0_e32 v2, v119
	v_cvt_f32_ubyte0_e32 v3, v0
	v_pk_mul_f32 v[28:29], v[28:29], v[34:35]
	v_pk_mul_f32 v[34:35], v[118:119], v[2:3] op_sel_hi:[0,1]
	v_or_b32_e32 v0, 3, v119
	v_or_b32_e32 v2, 2, v119
	v_cvt_f32_ubyte0_e32 v3, v0
	v_cvt_f32_ubyte0_e32 v2, v2
	v_pk_mul_f32 v[36:37], v[118:119], v[2:3] op_sel_hi:[0,1]
	v_or_b32_e32 v0, 9, v119
	v_or_b32_e32 v2, 8, v119
	v_cvt_f32_ubyte0_e32 v3, v0
	v_cvt_f32_ubyte0_e32 v2, v2
	v_pk_mul_f32 v[38:39], v[118:119], v[2:3] op_sel_hi:[0,1]
	v_or_b32_e32 v0, 11, v119
	v_or_b32_e32 v2, 10, v119
	v_cvt_f32_ubyte0_e32 v3, v0
	v_cvt_f32_ubyte0_e32 v2, v2
	v_or_b32_e32 v0, 17, v119
	v_or_b32_e32 v98, 16, v119
	v_pk_mul_f32 v[40:41], v[118:119], v[2:3] op_sel_hi:[0,1]
	v_cvt_f32_ubyte0_e32 v3, v0
	v_cvt_f32_ubyte0_e32 v2, v98
	v_pk_mul_f32 v[42:43], v[118:119], v[2:3] op_sel_hi:[0,1]
	v_or_b32_e32 v0, 19, v119
	v_or_b32_e32 v2, 18, v119
	v_cvt_f32_ubyte0_e32 v3, v0
	v_cvt_f32_ubyte0_e32 v2, v2
	v_pk_mul_f32 v[44:45], v[118:119], v[2:3] op_sel_hi:[0,1]
	v_or_b32_e32 v0, 25, v119
	v_or_b32_e32 v2, 24, v119
	v_cvt_f32_ubyte0_e32 v3, v0
	v_cvt_f32_ubyte0_e32 v2, v2
	v_or_b32_e32 v0, 27, v119
	v_pk_mul_f32 v[46:47], v[118:119], v[2:3] op_sel_hi:[0,1]
	v_cvt_f32_ubyte0_e32 v3, v0
	v_subrev_u32_e32 v0, 31, v66
	v_and_b32_e32 v172, 31, v106
	v_lshlrev_b32_e32 v173, 3, v170
	v_or_b32_e32 v2, 26, v119
	v_ashrrev_i32_e32 v0, 4, v0
	s_cmp_gt_u32 s79, 15
	v_and_b32_e32 v107, 63, v106
	v_pk_mul_f32 v[20:21], v[20:21], v[26:27]
	v_pk_mul_f32 v[12:13], v[12:13], v[18:19]
	v_pk_mul_f32 v[4:5], v[4:5], v[10:11]
	v_cvt_f32_ubyte0_e32 v2, v2
	v_sub_u32_e32 v103, v0, v119
	s_cselect_b64 s[4:5], -1, 0
	s_cmp_lt_u32 s79, 16
	v_mad_u32_u24 v0, v172, s34, v173
	v_cvt_pk_bf16_f32 v82, v30, v31
	v_cvt_pk_bf16_f32 v83, v32, v33
	v_cvt_pk_bf16_f32 v85, v28, v29
	v_cvt_pk_bf16_f32 v86, v22, v23
	v_cvt_pk_bf16_f32 v87, v24, v25
	v_cvt_pk_bf16_f32 v89, v20, v21
	v_cvt_pk_bf16_f32 v90, v14, v15
	v_cvt_pk_bf16_f32 v91, v16, v17
	v_cvt_pk_bf16_f32 v93, v12, v13
	v_cvt_pk_bf16_f32 v94, v6, v7
	v_cvt_pk_bf16_f32 v95, v8, v9
	v_cvt_pk_bf16_f32 v97, v4, v5
	v_pk_mul_f32 v[48:49], v[118:119], v[2:3] op_sel_hi:[0,1]
	s_cselect_b64 s[6:7], -1, 0
	v_mul_f32_e32 v99, 0x44000000, v118
	v_cmp_gt_u32_e64 s[0:1], 32, v107
	s_cmp_lt_u32 s15, 8
	v_lshl_add_u32 v100, v0, 1, 0
	s_waitcnt lgkmcnt(0)
	s_barrier
	s_cbranch_scc1 .LBB0_559
	ds_read_b128 v[2:5], v100 offset:32256
	ds_read_b128 v[6:9], v100 offset:32288
	ds_read_b128 v[10:13], v100 offset:32320
	ds_read_b128 v[50:53], v100 offset:32352
	s_waitcnt lgkmcnt(3)
	v_mfma_f32_32x32x16_bf16 v[18:33], v[2:5], v[82:85], 0
	s_mov_b64 s[2:3], -1
	s_cmpk_lt_u32 s79, 0x41
	s_waitcnt lgkmcnt(2)
	v_mfma_f32_32x32x16_bf16 v[18:33], v[6:9], v[86:89], v[18:33]
	s_waitcnt lgkmcnt(1)
	v_mfma_f32_32x32x16_bf16 v[18:33], v[10:13], v[90:93], v[18:33]
	s_waitcnt lgkmcnt(0)
	v_mfma_f32_32x32x16_bf16 v[18:33], v[50:53], v[94:97], v[18:33]
	s_cbranch_scc1 .LBB0_553
	s_nop 10
	v_pk_fma_f32 v[16:17], v[48:49], s[84:85], v[32:33] op_sel_hi:[1,0,1]
	v_pk_fma_f32 v[14:15], v[46:47], s[84:85], v[30:31] op_sel_hi:[1,0,1]
	v_pk_fma_f32 v[12:13], v[44:45], s[84:85], v[28:29] op_sel_hi:[1,0,1]
	v_pk_fma_f32 v[10:11], v[42:43], s[84:85], v[26:27] op_sel_hi:[1,0,1]
	v_pk_fma_f32 v[8:9], v[40:41], s[84:85], v[24:25] op_sel_hi:[1,0,1]
	v_pk_fma_f32 v[6:7], v[38:39], s[84:85], v[22:23] op_sel_hi:[1,0,1]
	v_pk_fma_f32 v[4:5], v[36:37], s[84:85], v[20:21] op_sel_hi:[1,0,1]
	v_pk_fma_f32 v[2:3], v[34:35], s[84:85], v[18:19] op_sel_hi:[1,0,1]
	s_mov_b64 s[2:3], 0

.Lp3_conv:
	v_readfirstlane_b32 s1, v202
	s_lshr_b32 s1, s1, 6
	s_lshl_b32 s52, s0, 3
	s_add_i32 s52, s52, s1
	s_lshl_b32 s20, s52, 4
	v_readlane_b32 s36, v248, 12
	v_readlane_b32 s37, v248, 13
	v_readlane_b32 s8, v249, 3
	v_readlane_b32 s9, v249, 4
	v_and_b32_e32 v2, 63, v202
	v_lshlrev_b32_e32 v3, 5, v2
	v_lshlrev_b32_e32 v2, 4, v2
	s_add_u32 s8, s8, 0x10000000
	s_addc_u32 s9, s9, 0
	s_lshl_b32 s10, s20, 11
	s_mul_i32 s11, s20, 0xc00
	s_add_u32 s12, s74, s10
	s_addc_u32 s13, s75, 0
	s_add_u32 s14, s8, s10
	s_addc_u32 s15, s9, 0
	s_add_u32 s16, s68, s11
	s_addc_u32 s17, s69, 0
	s_add_u32 s16, s16, 0x400
	s_addc_u32 s17, s17, 0
	s_and_b32 s21, s52, 0xff
	s_cmp_lg_u32 s21, 0
	s_cselect_b32 s22, 0xfffff800, 0
	s_cselect_b32 s23, -1, 0
	s_cselect_b32 s24, 0xfffff000, 0
	s_add_u32 s26, s12, s22
	s_addc_u32 s27, s13, s23
	s_add_u32 s28, s12, s24
	s_addc_u32 s29, s13, s23
	s_add_u32 s18, s36, 0x0
	s_addc_u32 s19, s37, 0
	global_load_dwordx4 v[132:135], v3, s[18:19]
	global_load_dwordx4 v[136:139], v3, s[18:19] offset:16
	s_add_u32 s18, s36, 0x1000
	s_addc_u32 s19, s37, 0
	global_load_dwordx4 v[140:143], v3, s[18:19]
	global_load_dwordx4 v[144:147], v3, s[18:19] offset:16
	s_add_u32 s18, s36, 0x2000
	s_addc_u32 s19, s37, 0
	global_load_dwordx4 v[148:151], v3, s[18:19]
	global_load_dwordx4 v[152:155], v3, s[18:19] offset:16
	s_add_u32 s18, s36, 0x800
	s_addc_u32 s19, s37, 0
	global_load_dwordx4 v[156:159], v3, s[18:19]
	global_load_dwordx4 v[160:163], v3, s[18:19] offset:16
	s_add_u32 s18, s36, 0x1800
	s_addc_u32 s19, s37, 0
	global_load_dwordx4 v[164:167], v3, s[18:19]
	global_load_dwordx4 v[168:171], v3, s[18:19] offset:16
	s_add_u32 s18, s36, 0x2800
	s_addc_u32 s19, s37, 0
	global_load_dwordx4 v[172:175], v3, s[18:19]
	global_load_dwordx4 v[176:179], v3, s[18:19] offset:16
	global_load_dwordx4 v[180:183], v2, s[26:27]
	global_load_dwordx4 v[184:187], v2, s[28:29]
	global_load_dwordx4 v[188:191], v2, s[26:27] offset:1024
	global_load_dwordx4 v[196:199], v2, s[28:29] offset:1024
	s_add_u32 s18, s12, 0x0
	s_addc_u32 s19, s13, 0
	s_add_u32 s30, s14, 0x0
	s_addc_u32 s31, s15, 0
	global_load_dwordx4 v[4:7], v2, s[18:19]
	global_load_dwordx4 v[36:39], v2, s[30:31]
	s_add_u32 s18, s12, 0x800
	s_addc_u32 s19, s13, 0
	s_add_u32 s30, s14, 0x800
	s_addc_u32 s31, s15, 0
	global_load_dwordx4 v[8:11], v2, s[18:19]
	global_load_dwordx4 v[40:43], v2, s[30:31]
	s_add_u32 s18, s12, 0x1000
	s_addc_u32 s19, s13, 0
	s_add_u32 s30, s14, 0x1000
	s_addc_u32 s31, s15, 0
	global_load_dwordx4 v[12:15], v2, s[18:19]
	global_load_dwordx4 v[44:47], v2, s[30:31]
	s_add_u32 s18, s12, 0x1800
	s_addc_u32 s19, s13, 0
	s_add_u32 s30, s14, 0x1800
	s_addc_u32 s31, s15, 0
	global_load_dwordx4 v[16:19], v2, s[18:19]
	global_load_dwordx4 v[48:51], v2, s[30:31]
	s_add_u32 s18, s12, 0x2000
	s_addc_u32 s19, s13, 0
	s_add_u32 s30, s14, 0x2000
	s_addc_u32 s31, s15, 0
	global_load_dwordx4 v[20:23], v2, s[18:19]
	global_load_dwordx4 v[52:55], v2, s[30:31]
	s_add_u32 s18, s12, 0x2800
	s_addc_u32 s19, s13, 0
	s_add_u32 s30, s14, 0x2800
	s_addc_u32 s31, s15, 0
	global_load_dwordx4 v[24:27], v2, s[18:19]
	global_load_dwordx4 v[56:59], v2, s[30:31]
	s_add_u32 s18, s12, 0x3000
	s_addc_u32 s19, s13, 0
	s_add_u32 s30, s14, 0x3000
	s_addc_u32 s31, s15, 0
	global_load_dwordx4 v[28:31], v2, s[18:19]
	global_load_dwordx4 v[60:63], v2, s[30:31]
	s_add_u32 s18, s12, 0x3800
	s_addc_u32 s19, s13, 0
	s_add_u32 s30, s14, 0x3800
	s_addc_u32 s31, s15, 0
	global_load_dwordx4 v[32:35], v2, s[18:19]
	global_load_dwordx4 v[64:67], v2, s[30:31]
	s_add_u32 s18, s12, 0x4000
	s_addc_u32 s19, s13, 0
	s_add_u32 s30, s14, 0x4000
	s_addc_u32 s31, s15, 0
	global_load_dwordx4 v[68:71], v2, s[18:19]
	global_load_dwordx4 v[100:103], v2, s[30:31]
	s_add_u32 s18, s12, 0x4800
	s_addc_u32 s19, s13, 0
	s_add_u32 s30, s14, 0x4800
	s_addc_u32 s31, s15, 0
	global_load_dwordx4 v[72:75], v2, s[18:19]
	global_load_dwordx4 v[104:107], v2, s[30:31]
	s_add_u32 s18, s12, 0x5000
	s_addc_u32 s19, s13, 0
	s_add_u32 s30, s14, 0x5000
	s_addc_u32 s31, s15, 0
	global_load_dwordx4 v[76:79], v2, s[18:19]
	global_load_dwordx4 v[108:111], v2, s[30:31]
	s_add_u32 s18, s12, 0x5800
	s_addc_u32 s19, s13, 0
	s_add_u32 s30, s14, 0x5800
	s_addc_u32 s31, s15, 0
	global_load_dwordx4 v[80:83], v2, s[18:19]
	global_load_dwordx4 v[112:115], v2, s[30:31]
	s_add_u32 s18, s12, 0x6000
	s_addc_u32 s19, s13, 0
	s_add_u32 s30, s14, 0x6000
	s_addc_u32 s31, s15, 0
	global_load_dwordx4 v[84:87], v2, s[18:19]
	global_load_dwordx4 v[116:119], v2, s[30:31]
	s_add_u32 s18, s12, 0x6800
	s_addc_u32 s19, s13, 0
	s_add_u32 s30, s14, 0x6800
	s_addc_u32 s31, s15, 0
	global_load_dwordx4 v[88:91], v2, s[18:19]
	global_load_dwordx4 v[120:123], v2, s[30:31]
	s_add_u32 s18, s12, 0x7000
	s_addc_u32 s19, s13, 0
	s_add_u32 s30, s14, 0x7000
	s_addc_u32 s31, s15, 0
	global_load_dwordx4 v[92:95], v2, s[18:19]
	global_load_dwordx4 v[124:127], v2, s[30:31]
	s_add_u32 s18, s12, 0x7800
	s_addc_u32 s19, s13, 0
	s_add_u32 s30, s14, 0x7800
	s_addc_u32 s31, s15, 0
	global_load_dwordx4 v[96:99], v2, s[18:19]
	global_load_dwordx4 v[128:131], v2, s[30:31]
	s_waitcnt vmcnt(16)
	v_readfirstlane_b32 s32, v203
	s_add_i32 s32, s88, s32
	s_nop 0
	v_mov_b32_e32 v200, s32
	s_cmp_lg_u32 s21, 0
	s_cbranch_scc1 .Lcv_nz0
	v_mov_b32_e32 v180, 0
	v_mov_b32_e32 v181, 0
	v_mov_b32_e32 v182, 0
	v_mov_b32_e32 v183, 0
	v_mov_b32_e32 v184, 0
	v_mov_b32_e32 v185, 0
	v_mov_b32_e32 v186, 0
	v_mov_b32_e32 v187, 0
